# v46 + attention step loops: second-half step head straightened (common path falls through: wait+barrier, K DMA, V DMA inline; tail variants out of line)
# speedup vs baseline: 1.0149x; 1.0149x over previous
.LBB0_797:
	s_and_b64 vcc, exec, s[22:23]
	s_cbranch_vccnz .LBB0_812
	s_waitcnt vmcnt(3) lgkmcnt(0)
	s_barrier
	s_add_i32 s29, s30, 2
	s_cmp_ge_i32 s29, s71
	s_cbranch_scc1 .LBB0_800
	s_mulk_i32 s50, 0x6000
	s_sub_i32 s4, s56, s50
	s_add_i32 s4, s14, s4
	s_addk_i32 s4, 0xc000
	v_lshl_add_u64 v[68:69], v[192:193], 0, s[44:45]
	s_mov_b32 m0, s4
	s_nop 0
	global_load_lds_dwordx4 v[68:69], off
	s_andn2_b64 vcc, exec, s[94:95]
	s_cbranch_vccnz .LBB0_802

.LBB0_812:
	s_mov_b64 s[4:5], -1
	s_and_b64 vcc, exec, s[96:97]
	s_cbranch_vccz .LBB0_814
	s_waitcnt vmcnt(0) lgkmcnt(0)
	s_barrier
	s_mov_b64 s[4:5], 0

.LBB0_816:
	s_cbranch_execnz .LBB0_799
.LBB0_799:
	s_add_i32 s29, s30, 2
	s_cmp_ge_i32 s29, s71
	s_cbranch_scc0 .LBB0_818
.LBB0_800:
	s_andn2_b64 vcc, exec, s[94:95]
	s_cbranch_vccnz .LBB0_802
	s_branch .LBB0_801

.LBB0_865:
	s_and_b64 vcc, exec, s[22:23]
	s_cbranch_vccnz .LBB0_880
	s_waitcnt vmcnt(3) lgkmcnt(0)
	s_barrier
	s_add_i32 s29, s30, 2
	s_cmp_ge_i32 s29, s71
	s_cbranch_scc1 .LBB0_868
	s_mulk_i32 s50, 0x6000
	s_sub_i32 s4, s25, s50
	s_add_i32 s4, s14, s4
	s_addk_i32 s4, 0xc000
	v_lshl_add_u64 v[68:69], v[192:193], 0, s[44:45]
	s_mov_b32 m0, s4
	s_nop 0
	global_load_lds_dwordx4 v[68:69], off
	s_andn2_b64 vcc, exec, s[76:77]
	s_cbranch_vccnz .LBB0_870

.LBB0_880:
	s_mov_b64 s[4:5], -1
	s_and_b64 vcc, exec, s[80:81]
	s_cbranch_vccz .LBB0_882
	s_waitcnt vmcnt(0) lgkmcnt(0)
	s_barrier
	s_mov_b64 s[4:5], 0

.LBB0_884:
	s_cbranch_execnz .LBB0_867
.LBB0_867:
	s_add_i32 s29, s30, 2
	s_cmp_ge_i32 s29, s71
	s_cbranch_scc0 .LBB0_886
.LBB0_868:
	s_andn2_b64 vcc, exec, s[76:77]
	s_cbranch_vccnz .LBB0_870
	s_branch .LBB0_869
